# in-place softmax with 8 scalar v_sub instead of 4 packed adds (packed f32 ops are not cheaper beside MFMAs)
# baseline (speedup 1.0000x reference)
.LBB0_348:
	v_sub_f32_e32 v136, v136, v169
	v_sub_f32_e32 v137, v137, v169
	v_sub_f32_e32 v138, v138, v169
	v_sub_f32_e32 v139, v139, v169
	v_sub_f32_e32 v140, v140, v169
	v_sub_f32_e32 v141, v141, v169
	v_sub_f32_e32 v142, v142, v169
	v_sub_f32_e32 v143, v143, v169
	v_exp_f32_e32 v136, v136
	v_exp_f32_e32 v137, v137
	v_exp_f32_e32 v138, v138
	v_exp_f32_e32 v139, v139
	v_exp_f32_e32 v140, v140
	v_exp_f32_e32 v141, v141
	v_exp_f32_e32 v142, v142
	v_exp_f32_e32 v143, v143
	v_mov_b32_e32 v37, v36
	v_mov_b32_e32 v38, v36
	v_mov_b32_e32 v39, v36
	v_cvt_pk_bf16_f32 v136, v136, v137
	v_cvt_pk_bf16_f32 v137, v138, v139
	v_cvt_pk_bf16_f32 v138, v140, v141
	v_cvt_pk_bf16_f32 v139, v142, v143
	s_nop 1
	v_mfma_f32_16x16x32_bf16 v[52:55], v[120:123], v[136:139], v[52:55]
	v_mfma_f32_16x16x32_bf16 v[48:51], v[124:127], v[136:139], v[48:51]
	v_mfma_f32_16x16x32_bf16 v[44:47], v[128:131], v[136:139], v[44:47]
	v_mfma_f32_16x16x32_bf16 v[40:43], v[132:135], v[136:139], v[40:43]
	v_mfma_f32_16x16x32_bf16 v[56:59], v[36:39], v[136:139], v[56:59]
	s_add_u32 s34, s34, 0x10000
	s_addc_u32 s35, s35, 0
	s_add_i32 s30, s30, 2
	s_cmp_lg_u32 s34, 0x80000
	v_add_u32_e32 v212, 0x7c, v212
	s_cbranch_scc0 .LBB0_361

.LBB0_351:
	v_sub_f32_e32 v222, v222, v170
	v_sub_f32_e32 v223, v223, v170
	v_sub_f32_e32 v224, v224, v170
	v_sub_f32_e32 v225, v225, v170
	v_sub_f32_e32 v216, v216, v170
	v_sub_f32_e32 v217, v217, v170
	v_sub_f32_e32 v218, v218, v170
	v_sub_f32_e32 v219, v219, v170
	v_exp_f32_e32 v222, v222
	v_exp_f32_e32 v223, v223
	v_exp_f32_e32 v224, v224
	v_exp_f32_e32 v225, v225
	v_exp_f32_e32 v216, v216
	v_exp_f32_e32 v217, v217
	v_exp_f32_e32 v218, v218
	v_exp_f32_e32 v219, v219
	v_mov_b32_e32 v37, v36
	v_mov_b32_e32 v38, v36
	v_mov_b32_e32 v39, v36
	v_cvt_pk_bf16_f32 v214, v222, v223
	v_cvt_pk_bf16_f32 v215, v224, v225
	v_cvt_pk_bf16_f32 v216, v216, v217
	v_cvt_pk_bf16_f32 v217, v218, v219
	s_waitcnt vmcnt(11)
	s_nop 0
	v_mfma_f32_16x16x32_bf16 v[72:75], v[0:3], v[214:217], v[72:75]
	s_waitcnt vmcnt(10)
	v_mfma_f32_16x16x32_bf16 v[68:71], v[4:7], v[214:217], v[68:71]
	s_waitcnt vmcnt(9)
	v_mfma_f32_16x16x32_bf16 v[64:67], v[8:11], v[214:217], v[64:67]
	s_waitcnt vmcnt(8)
	v_mfma_f32_16x16x32_bf16 v[60:63], v[12:15], v[214:217], v[60:63]
	v_mfma_f32_16x16x32_bf16 v[76:79], v[36:39], v[214:217], v[76:79]
	ds_read_b128 v[214:217], v168 offset:22528
	ds_read_b128 v[218:221], v168 offset:23552
	ds_read_b32 v222, v212 offset:64
	ds_read_b32 v246, v212 offset:128
	ds_read_b32 v223, v212 offset:68
	ds_read_b32 v247, v212 offset:132
	ds_read_b32 v224, v212 offset:72
	ds_read_b32 v248, v212 offset:136
	ds_read_b32 v225, v212 offset:76
	ds_read_b32 v249, v212 offset:140
	s_waitcnt lgkmcnt(1)
	v_mfma_f32_16x16x32_bf16 v[222:225], v[24:27], v[214:217], v[222:225]
	s_waitcnt lgkmcnt(0)
	v_mfma_f32_16x16x32_bf16 v[214:217], v[28:31], v[214:217], v[246:249]
	v_mfma_f32_16x16x32_bf16 v[214:217], v[20:23], v[218:221], v[214:217]
	v_mfma_f32_16x16x32_bf16 v[222:225], v[16:19], v[218:221], v[222:225]
	s_nop 5
	s_nop 0
	v_bfi_b32 v214, v173, v214, s29
	v_bfi_b32 v215, v174, v215, s29
	v_bfi_b32 v222, v156, v222, s29
	v_bfi_b32 v223, v157, v223, s29
	v_bfi_b32 v216, v175, v216, s29
	v_bfi_b32 v224, v158, v224, s29
	v_bfi_b32 v225, v159, v225, s29
	v_bfi_b32 v217, v176, v217, s29
	v_max3_f32 v218, v214, v215, v222
	v_max3_f32 v220, v223, v216, v224
	v_max3_f32 v218, v218, v225, v217
	v_max_f32_e32 v218, v218, v220
	v_add_f32_e32 v219, 0x41000000, v172
	v_cmp_gt_f32_e32 vcc, v218, v219
	s_cbranch_vccz .LBB0_353
	v_mov_b32_e32 v219, v218
	s_nop 1
	v_permlane16_swap_b32 v218, v219
	s_nop 0
	v_max_f32_e32 v219, v219, v219
	v_max_f32_e32 v218, v218, v218
	v_max_f32_e32 v218, v218, v219
	v_mov_b32_e32 v219, v218
	s_nop 1
	v_permlane32_swap_b32 v218, v219
	s_nop 0
	v_max3_f32 v218, v172, v218, v219
	v_sub_f32_e32 v172, v172, v218
	v_exp_f32_e32 v172, v172
	s_nop 0
	v_pk_mul_f32 v[114:115], v[114:115], v[172:173] op_sel_hi:[1,0]
	v_pk_mul_f32 v[112:113], v[112:113], v[172:173] op_sel_hi:[1,0]
	v_pk_mul_f32 v[110:111], v[110:111], v[172:173] op_sel_hi:[1,0]
	v_pk_mul_f32 v[108:109], v[108:109], v[172:173] op_sel_hi:[1,0]
	v_pk_mul_f32 v[106:107], v[106:107], v[172:173] op_sel_hi:[1,0]
	v_pk_mul_f32 v[104:105], v[104:105], v[172:173] op_sel_hi:[1,0]
	v_pk_mul_f32 v[102:103], v[102:103], v[172:173] op_sel_hi:[1,0]
	v_pk_mul_f32 v[100:101], v[100:101], v[172:173] op_sel_hi:[1,0]
	v_pk_mul_f32 v[118:119], v[118:119], v[172:173] op_sel_hi:[1,0]
	v_pk_mul_f32 v[116:117], v[116:117], v[172:173] op_sel_hi:[1,0]
	v_mov_b32_e32 v172, v218
.LBB0_353:
	v_sub_f32_e32 v216, v216, v172
	v_sub_f32_e32 v217, v217, v172
	v_sub_f32_e32 v214, v214, v172
	v_sub_f32_e32 v215, v215, v172
	v_sub_f32_e32 v222, v222, v172
	v_sub_f32_e32 v223, v223, v172
	v_sub_f32_e32 v224, v224, v172
	v_sub_f32_e32 v225, v225, v172
	v_exp_f32_e32 v216, v216
	v_exp_f32_e32 v217, v217
	v_exp_f32_e32 v214, v214
	v_exp_f32_e32 v215, v215
	v_exp_f32_e32 v222, v222
	v_exp_f32_e32 v223, v223
	v_exp_f32_e32 v224, v224
	v_exp_f32_e32 v225, v225
	v_cvt_pk_bf16_f32 v217, v216, v217
	v_cvt_pk_bf16_f32 v216, v214, v215
	v_cvt_pk_bf16_f32 v214, v222, v223
	v_cvt_pk_bf16_f32 v215, v224, v225
	s_nop 1
	v_mfma_f32_16x16x32_bf16 v[112:115], v[0:3], v[214:217], v[112:115]
	v_mfma_f32_16x16x32_bf16 v[108:111], v[4:7], v[214:217], v[108:111]
	v_mfma_f32_16x16x32_bf16 v[104:107], v[8:11], v[214:217], v[104:107]
	v_mfma_f32_16x16x32_bf16 v[100:103], v[12:15], v[214:217], v[100:103]
	v_mfma_f32_16x16x32_bf16 v[116:119], v[36:39], v[214:217], v[116:119]
	ds_read_b128 v[214:217], v168 offset:24576
	ds_read_b128 v[218:221], v168 offset:25600
	ds_read_b32 v222, v212
	ds_read_b32 v246, v212 offset:64
	ds_read_b32 v223, v212 offset:4
	ds_read_b32 v247, v212 offset:68
	ds_read_b32 v224, v212 offset:8
	ds_read_b32 v248, v212 offset:72
	ds_read_b32 v225, v212 offset:12
	ds_read_b32 v249, v212 offset:76
	s_waitcnt lgkmcnt(1)
	v_mfma_f32_16x16x32_bf16 v[24:27], v[24:27], v[214:217], v[222:225]
	v_mfma_f32_16x16x32_bf16 v[16:19], v[16:19], v[218:221], v[24:27]
	s_waitcnt lgkmcnt(0)
	s_nop 5
	v_mfma_f32_16x16x32_bf16 v[24:27], v[28:31], v[214:217], v[246:249]
	v_mfma_f32_16x16x32_bf16 v[20:23], v[20:23], v[218:221], v[24:27]
	s_nop 4
	v_cndmask_b32_e64 v16, v242, v16, s[58:59]
	s_nop 0
	v_bfi_b32 v17, v177, v17, s29
	v_bfi_b32 v18, v178, v18, s29
	v_bfi_b32 v19, v183, v19, s29
	v_bfi_b32 v20, v184, v20, s29
	v_bfi_b32 v21, v185, v21, s29
	v_bfi_b32 v22, v186, v22, s29
	v_bfi_b32 v23, v187, v23, s29
	v_max3_f32 v24, v16, v17, v18
	v_max3_f32 v26, v19, v20, v21
	v_max3_f32 v24, v24, v22, v23
	v_max_f32_e32 v24, v24, v26
	v_add_f32_e32 v25, 0x41000000, v171
	v_cmp_gt_f32_e32 vcc, v24, v25
	s_cbranch_vccz .LBB0_355
	v_mov_b32_e32 v25, v24
	s_nop 1
	v_permlane16_swap_b32 v24, v25
	s_nop 0
	v_max_f32_e32 v25, v25, v25
	v_max_f32_e32 v24, v24, v24
	v_max_f32_e32 v24, v24, v25
	v_mov_b32_e32 v25, v24
	s_nop 1
	v_permlane32_swap_b32 v24, v25
	s_nop 0
	v_max3_f32 v25, v171, v24, v25
	v_sub_f32_e32 v24, v171, v25
	v_exp_f32_e32 v24, v24
	v_mov_b32_e32 v171, v25
	v_pk_mul_f32 v[94:95], v[94:95], v[24:25] op_sel_hi:[1,0]
	v_pk_mul_f32 v[92:93], v[92:93], v[24:25] op_sel_hi:[1,0]
	v_pk_mul_f32 v[90:91], v[90:91], v[24:25] op_sel_hi:[1,0]
	v_pk_mul_f32 v[88:89], v[88:89], v[24:25] op_sel_hi:[1,0]
	v_pk_mul_f32 v[86:87], v[86:87], v[24:25] op_sel_hi:[1,0]
	v_pk_mul_f32 v[84:85], v[84:85], v[24:25] op_sel_hi:[1,0]
	v_pk_mul_f32 v[82:83], v[82:83], v[24:25] op_sel_hi:[1,0]
	v_pk_mul_f32 v[80:81], v[80:81], v[24:25] op_sel_hi:[1,0]
	v_pk_mul_f32 v[98:99], v[98:99], v[24:25] op_sel_hi:[1,0]
	v_pk_mul_f32 v[96:97], v[96:97], v[24:25] op_sel_hi:[1,0]
.LBB0_355:
	v_sub_f32_e32 v16, v16, v171
	v_sub_f32_e32 v17, v17, v171
	v_sub_f32_e32 v18, v18, v171
	v_sub_f32_e32 v19, v19, v171
	v_sub_f32_e32 v20, v20, v171
	v_sub_f32_e32 v21, v21, v171
	v_sub_f32_e32 v22, v22, v171
	v_sub_f32_e32 v23, v23, v171
	v_exp_f32_e32 v16, v16
	v_exp_f32_e32 v17, v17
	v_exp_f32_e32 v18, v18
	v_exp_f32_e32 v19, v19
	v_exp_f32_e32 v20, v20
	v_exp_f32_e32 v21, v21
	v_exp_f32_e32 v22, v22
	v_exp_f32_e32 v23, v23
	v_cvt_pk_bf16_f32 v16, v16, v17
	v_cvt_pk_bf16_f32 v17, v18, v19
	v_cvt_pk_bf16_f32 v18, v20, v21
	v_cvt_pk_bf16_f32 v19, v22, v23
	s_nop 1
	v_mfma_f32_16x16x32_bf16 v[92:95], v[0:3], v[16:19], v[92:95]
	v_mfma_f32_16x16x32_bf16 v[88:91], v[4:7], v[16:19], v[88:91]
	v_mfma_f32_16x16x32_bf16 v[84:87], v[8:11], v[16:19], v[84:87]
	v_mfma_f32_16x16x32_bf16 v[80:83], v[12:15], v[16:19], v[80:83]
	v_mfma_f32_16x16x32_bf16 v[96:99], v[36:39], v[16:19], v[96:99]
	s_cmp_eq_u32 s34, 0x70000
	s_cselect_b32 s40, s60, s30
	s_lshl_b32 s0, s40, 1
	s_lshl_b64 s[60:61], s[0:1], 14
	v_lshl_add_u64 v[0:1], v[164:165], 0, s[60:61]
	s_mov_b32 s41, s1
	s_lshl_b64 s[40:41], s[40:41], 15
	global_load_dwordx4 v[24:27], v[0:1], off
	global_load_dwordx4 v[16:19], v[0:1], off offset:1024
	v_add_co_u32_e32 v0, vcc, s72, v0
	v_lshl_add_u64 v[12:13], v[166:167], 0, s[40:41]
	s_nop 0
	v_addc_co_u32_e32 v1, vcc, 0, v1, vcc
	global_load_dwordx4 v[28:31], v[0:1], off
	global_load_dwordx4 v[20:23], v[0:1], off offset:1024
	s_nop 0
	global_load_dwordx4 v[0:3], v[12:13], off
	global_load_dwordx4 v[4:7], v[12:13], off offset:1024
	global_load_dwordx4 v[8:11], v[12:13], off offset:2048
	s_nop 0
	global_load_dwordx4 v[12:15], v[12:13], off offset:3072
	ds_read_b128 v[214:217], v168 offset:22528
	ds_read_b128 v[218:221], v168 offset:23552
	ds_read_b32 v222, v212 offset:192
	ds_read_b32 v246, v212 offset:256
	ds_read_b32 v223, v212 offset:196
	ds_read_b32 v247, v212 offset:260
	ds_read_b32 v224, v212 offset:200
	ds_read_b32 v248, v212 offset:264
	ds_read_b32 v225, v212 offset:204
	ds_read_b32 v249, v212 offset:268
	s_waitcnt vmcnt(15) lgkmcnt(1)
	v_mfma_f32_16x16x32_bf16 v[222:225], v[136:139], v[214:217], v[222:225]
	s_waitcnt vmcnt(13) lgkmcnt(0)
	v_mfma_f32_16x16x32_bf16 v[214:217], v[148:151], v[214:217], v[246:249]
	s_waitcnt vmcnt(12)
	v_mfma_f32_16x16x32_bf16 v[214:217], v[144:147], v[218:221], v[214:217]
	v_mfma_f32_16x16x32_bf16 v[222:225], v[140:143], v[218:221], v[222:225]
	s_nop 5
	s_nop 0
	v_bfi_b32 v214, v192, v214, s29
	v_bfi_b32 v215, v193, v215, s29
	v_bfi_b32 v222, v188, v222, s29
	v_bfi_b32 v223, v189, v223, s29
	v_bfi_b32 v216, v194, v216, s29
	v_bfi_b32 v224, v190, v224, s29
	v_bfi_b32 v225, v191, v225, s29
	v_bfi_b32 v217, v195, v217, s29
	v_max3_f32 v218, v214, v215, v222
	v_max3_f32 v220, v223, v216, v224
	v_max3_f32 v218, v218, v225, v217
	v_max_f32_e32 v218, v218, v220
	v_add_f32_e32 v219, 0x41000000, v172
	v_cmp_gt_f32_e32 vcc, v218, v219
	s_cbranch_vccz .LBB0_357
	v_mov_b32_e32 v219, v218
	s_nop 1
	v_permlane16_swap_b32 v218, v219
	s_nop 0
	v_max_f32_e32 v219, v219, v219
	v_max_f32_e32 v218, v218, v218
	v_max_f32_e32 v218, v218, v219
	v_mov_b32_e32 v219, v218
	s_nop 1
	v_permlane32_swap_b32 v219, v218
	s_nop 0
	v_max3_f32 v218, v172, v219, v218
	v_sub_f32_e32 v172, v172, v218
	v_exp_f32_e32 v172, v172
	s_nop 0
	v_pk_mul_f32 v[114:115], v[114:115], v[172:173] op_sel_hi:[1,0]
	v_pk_mul_f32 v[112:113], v[112:113], v[172:173] op_sel_hi:[1,0]
	v_pk_mul_f32 v[110:111], v[110:111], v[172:173] op_sel_hi:[1,0]
	v_pk_mul_f32 v[108:109], v[108:109], v[172:173] op_sel_hi:[1,0]
	v_pk_mul_f32 v[106:107], v[106:107], v[172:173] op_sel_hi:[1,0]
	v_pk_mul_f32 v[104:105], v[104:105], v[172:173] op_sel_hi:[1,0]
	v_pk_mul_f32 v[102:103], v[102:103], v[172:173] op_sel_hi:[1,0]
	v_pk_mul_f32 v[100:101], v[100:101], v[172:173] op_sel_hi:[1,0]
	v_pk_mul_f32 v[118:119], v[118:119], v[172:173] op_sel_hi:[1,0]
	v_pk_mul_f32 v[116:117], v[116:117], v[172:173] op_sel_hi:[1,0]
	v_mov_b32_e32 v172, v218
.LBB0_357:
	v_sub_f32_e32 v216, v216, v172
	v_sub_f32_e32 v217, v217, v172
	v_sub_f32_e32 v214, v214, v172
	v_sub_f32_e32 v215, v215, v172
	v_sub_f32_e32 v222, v222, v172
	v_sub_f32_e32 v223, v223, v172
	v_sub_f32_e32 v224, v224, v172
	v_sub_f32_e32 v225, v225, v172
	v_exp_f32_e32 v216, v216
	v_exp_f32_e32 v217, v217
	v_exp_f32_e32 v214, v214
	v_exp_f32_e32 v215, v215
	v_exp_f32_e32 v222, v222
	v_exp_f32_e32 v223, v223
	v_exp_f32_e32 v224, v224
	v_exp_f32_e32 v225, v225
	v_cvt_pk_bf16_f32 v217, v216, v217
	v_cvt_pk_bf16_f32 v216, v214, v215
	v_cvt_pk_bf16_f32 v214, v222, v223
	v_cvt_pk_bf16_f32 v215, v224, v225
	s_waitcnt vmcnt(11)
	s_nop 0
	v_mfma_f32_16x16x32_bf16 v[112:115], v[120:123], v[214:217], v[112:115]
	s_waitcnt vmcnt(10)
	v_mfma_f32_16x16x32_bf16 v[108:111], v[124:127], v[214:217], v[108:111]
	s_waitcnt vmcnt(9)
	v_mfma_f32_16x16x32_bf16 v[104:107], v[128:131], v[214:217], v[104:107]
	s_waitcnt vmcnt(8)
	v_mfma_f32_16x16x32_bf16 v[100:103], v[132:135], v[214:217], v[100:103]
	v_mfma_f32_16x16x32_bf16 v[116:119], v[36:39], v[214:217], v[116:119]
	ds_read_b128 v[214:217], v168 offset:24576
	ds_read_b128 v[218:221], v168 offset:25600
	ds_read_b32 v222, v212 offset:128
	ds_read_b32 v246, v212 offset:192
	ds_read_b32 v223, v212 offset:132
	ds_read_b32 v247, v212 offset:196
	ds_read_b32 v224, v212 offset:136
	ds_read_b32 v248, v212 offset:200
	ds_read_b32 v225, v212 offset:140
	ds_read_b32 v249, v212 offset:204
	s_waitcnt lgkmcnt(1)
	v_mfma_f32_16x16x32_bf16 v[222:225], v[136:139], v[214:217], v[222:225]
	s_waitcnt lgkmcnt(0)
	v_mfma_f32_16x16x32_bf16 v[214:217], v[148:151], v[214:217], v[246:249]
	v_readlane_b32 s60, v252, 47
	v_mfma_f32_16x16x32_bf16 v[222:225], v[140:143], v[218:221], v[222:225]
	v_mfma_f32_16x16x32_bf16 v[214:217], v[144:147], v[218:221], v[214:217]
	s_nop 6
	v_bfi_b32 v222, v196, v222, s29
	v_bfi_b32 v223, v197, v223, s29
	v_bfi_b32 v224, v198, v224, s29
	v_bfi_b32 v225, v199, v225, s29
	v_bfi_b32 v214, v200, v214, s29
	v_bfi_b32 v215, v201, v215, s29
	v_bfi_b32 v216, v202, v216, s29
	v_bfi_b32 v217, v203, v217, s29
	v_max3_f32 v32, v222, v223, v224
	v_max3_f32 v35, v225, v214, v215
	v_max3_f32 v32, v32, v216, v217
	v_max_f32_e32 v32, v32, v35
	v_add_f32_e32 v34, 0x41000000, v171
	v_cmp_gt_f32_e32 vcc, v32, v34
	s_cbranch_vccz .LBB0_359
	v_mov_b32_e32 v34, v32
	s_nop 1
	v_permlane16_swap_b32 v32, v34
	s_nop 0
	v_max_f32_e32 v34, v34, v34
	v_max_f32_e32 v32, v32, v32
	v_max_f32_e32 v32, v32, v34
	v_mov_b32_e32 v34, v32
	s_nop 1
	v_permlane32_swap_b32 v32, v34
	s_nop 0
	v_max3_f32 v32, v171, v32, v34
	v_sub_f32_e32 v171, v171, v32
	v_exp_f32_e32 v34, v171
	v_mov_b32_e32 v171, v32
	v_pk_mul_f32 v[94:95], v[94:95], v[34:35] op_sel_hi:[1,0]
	v_pk_mul_f32 v[92:93], v[92:93], v[34:35] op_sel_hi:[1,0]
	v_pk_mul_f32 v[90:91], v[90:91], v[34:35] op_sel_hi:[1,0]
	v_pk_mul_f32 v[88:89], v[88:89], v[34:35] op_sel_hi:[1,0]
	v_pk_mul_f32 v[86:87], v[86:87], v[34:35] op_sel_hi:[1,0]
	v_pk_mul_f32 v[84:85], v[84:85], v[34:35] op_sel_hi:[1,0]
	v_pk_mul_f32 v[82:83], v[82:83], v[34:35] op_sel_hi:[1,0]
	v_pk_mul_f32 v[80:81], v[80:81], v[34:35] op_sel_hi:[1,0]
	v_pk_mul_f32 v[98:99], v[98:99], v[34:35] op_sel_hi:[1,0]
	v_pk_mul_f32 v[96:97], v[96:97], v[34:35] op_sel_hi:[1,0]
.LBB0_359:
	v_sub_f32_e32 v216, v216, v171
	v_sub_f32_e32 v217, v217, v171
	v_sub_f32_e32 v214, v214, v171
	v_sub_f32_e32 v215, v215, v171
	v_sub_f32_e32 v222, v222, v171
	v_sub_f32_e32 v223, v223, v171
	v_sub_f32_e32 v224, v224, v171
	v_sub_f32_e32 v225, v225, v171
	v_exp_f32_e32 v216, v216
	v_exp_f32_e32 v217, v217
	v_exp_f32_e32 v214, v214
	v_exp_f32_e32 v215, v215
	v_exp_f32_e32 v222, v222
	v_exp_f32_e32 v223, v223
	v_exp_f32_e32 v224, v224
	v_exp_f32_e32 v225, v225
	v_cvt_pk_bf16_f32 v217, v216, v217
	v_cvt_pk_bf16_f32 v216, v214, v215
	v_cvt_pk_bf16_f32 v214, v222, v223
	v_cvt_pk_bf16_f32 v215, v224, v225
	s_nop 1
	v_mfma_f32_16x16x32_bf16 v[92:95], v[120:123], v[214:217], v[92:95]
	v_mfma_f32_16x16x32_bf16 v[88:91], v[124:127], v[214:217], v[88:91]
	v_mfma_f32_16x16x32_bf16 v[84:87], v[128:131], v[214:217], v[84:87]
	v_mfma_f32_16x16x32_bf16 v[80:83], v[132:135], v[214:217], v[80:83]
	v_mfma_f32_16x16x32_bf16 v[96:99], v[36:39], v[214:217], v[96:99]
	ds_read_b128 v[214:217], v168 offset:26624
	ds_read_b128 v[218:221], v168 offset:27648
	ds_read_b32 v222, v212 offset:64
	ds_read_b32 v246, v212 offset:128
	ds_read_b32 v223, v212 offset:68
	ds_read_b32 v247, v212 offset:132
	ds_read_b32 v224, v212 offset:72
	ds_read_b32 v248, v212 offset:136
	ds_read_b32 v225, v212 offset:76
	ds_read_b32 v249, v212 offset:140
	s_waitcnt lgkmcnt(1)
	v_mfma_f32_16x16x32_bf16 v[136:139], v[136:139], v[214:217], v[222:225]
	v_mfma_f32_16x16x32_bf16 v[136:139], v[140:143], v[218:221], v[136:139]
	s_waitcnt lgkmcnt(0)
	v_mfma_f32_16x16x32_bf16 v[140:143], v[148:151], v[214:217], v[246:249]
	v_mfma_f32_16x16x32_bf16 v[140:143], v[144:147], v[218:221], v[140:143]
	s_nop 4
	v_bfi_b32 v136, v204, v136, s29
	v_bfi_b32 v137, v205, v137, s29
	v_bfi_b32 v138, v206, v138, s29
	v_bfi_b32 v139, v207, v139, s29
	v_bfi_b32 v140, v208, v140, s29
	v_bfi_b32 v141, v209, v141, s29
	v_bfi_b32 v142, v210, v142, s29
	v_bfi_b32 v143, v211, v143, s29
	v_max3_f32 v32, v136, v137, v138
	v_max3_f32 v35, v139, v140, v141
	v_max3_f32 v32, v32, v142, v143
	v_max_f32_e32 v32, v32, v35
	v_add_f32_e32 v34, 0x41000000, v169
	v_cmp_gt_f32_e32 vcc, v32, v34
	s_cbranch_vccz .LBB0_348
	v_mov_b32_e32 v34, v32
	s_nop 1
	v_permlane16_swap_b32 v32, v34
	s_nop 0
	v_max_f32_e32 v34, v34, v34
	v_max_f32_e32 v32, v32, v32
	v_max_f32_e32 v32, v32, v34
	v_mov_b32_e32 v34, v32
	s_nop 1
	v_permlane32_swap_b32 v32, v34
	s_nop 0
	v_max3_f32 v32, v169, v32, v34
	v_sub_f32_e32 v34, v169, v32
	v_exp_f32_e32 v34, v34
	v_mov_b32_e32 v169, v32
	v_pk_mul_f32 v[54:55], v[54:55], v[34:35] op_sel_hi:[1,0]
	v_pk_mul_f32 v[52:53], v[52:53], v[34:35] op_sel_hi:[1,0]
	v_pk_mul_f32 v[50:51], v[50:51], v[34:35] op_sel_hi:[1,0]
	v_pk_mul_f32 v[48:49], v[48:49], v[34:35] op_sel_hi:[1,0]
	v_pk_mul_f32 v[46:47], v[46:47], v[34:35] op_sel_hi:[1,0]
	v_pk_mul_f32 v[44:45], v[44:45], v[34:35] op_sel_hi:[1,0]
	v_pk_mul_f32 v[42:43], v[42:43], v[34:35] op_sel_hi:[1,0]
	v_pk_mul_f32 v[40:41], v[40:41], v[34:35] op_sel_hi:[1,0]
	v_pk_mul_f32 v[58:59], v[58:59], v[34:35] op_sel_hi:[1,0]
	v_pk_mul_f32 v[56:57], v[56:57], v[34:35] op_sel_hi:[1,0]
	s_branch .LBB0_348

.LBB0_362:
	v_sub_f32_e32 v138, v138, v169
	v_sub_f32_e32 v139, v139, v169
	v_sub_f32_e32 v136, v136, v169
	v_sub_f32_e32 v137, v137, v169
	v_sub_f32_e32 v140, v140, v169
	v_sub_f32_e32 v141, v141, v169
	v_sub_f32_e32 v142, v142, v169
	v_sub_f32_e32 v143, v143, v169
	v_exp_f32_e32 v138, v138
	v_exp_f32_e32 v139, v139
	v_exp_f32_e32 v136, v136
	v_exp_f32_e32 v137, v137
	v_exp_f32_e32 v140, v140
	v_exp_f32_e32 v141, v141
	v_exp_f32_e32 v142, v142
	v_exp_f32_e32 v143, v143
	v_mov_b32_e32 v37, v36
	v_mov_b32_e32 v38, v36
	v_mov_b32_e32 v39, v36
	v_cvt_pk_bf16_f32 v139, v138, v139
	v_cvt_pk_bf16_f32 v138, v136, v137
	v_cvt_pk_bf16_f32 v136, v140, v141
	v_cvt_pk_bf16_f32 v137, v142, v143
	s_nop 1
	v_mfma_f32_16x16x32_bf16 v[52:55], v[120:123], v[136:139], v[52:55]
	v_mfma_f32_16x16x32_bf16 v[48:51], v[124:127], v[136:139], v[48:51]
	v_mfma_f32_16x16x32_bf16 v[44:47], v[128:131], v[136:139], v[44:47]
	v_mfma_f32_16x16x32_bf16 v[40:43], v[132:135], v[136:139], v[40:43]
	v_mfma_f32_16x16x32_bf16 v[56:59], v[36:39], v[136:139], v[56:59]
	s_add_i32 s30, s30, 2
	s_add_u32 s24, s24, 0x10000
	s_addc_u32 s25, s25, 0
	s_add_u32 s26, s26, 0x10000
	s_addc_u32 s27, s27, 0
	s_cmp_lt_u32 s31, 6
	s_cbranch_scc0 .LBB0_379

.LBB0_365:
	v_sub_f32_e32 v152, v152, v170
	v_sub_f32_e32 v153, v153, v170
	v_sub_f32_e32 v154, v154, v170
	v_sub_f32_e32 v155, v155, v170
	v_sub_f32_e32 v156, v156, v170
	v_sub_f32_e32 v157, v157, v170
	v_sub_f32_e32 v158, v158, v170
	v_sub_f32_e32 v159, v159, v170
	v_exp_f32_e32 v152, v152
	v_exp_f32_e32 v153, v153
	v_exp_f32_e32 v154, v154
	v_exp_f32_e32 v155, v155
	v_exp_f32_e32 v156, v156
	v_exp_f32_e32 v157, v157
	v_exp_f32_e32 v158, v158
	v_exp_f32_e32 v159, v159
	v_mov_b32_e32 v37, v36
	v_mov_b32_e32 v38, v36
	v_mov_b32_e32 v39, v36
	v_cvt_pk_bf16_f32 v152, v152, v153
	v_cvt_pk_bf16_f32 v153, v154, v155
	v_cvt_pk_bf16_f32 v154, v156, v157
	v_cvt_pk_bf16_f32 v155, v158, v159
	s_waitcnt vmcnt(11)
	s_nop 0
	v_mfma_f32_16x16x32_bf16 v[72:75], v[0:3], v[152:155], v[72:75]
	s_waitcnt vmcnt(10)
	v_mfma_f32_16x16x32_bf16 v[68:71], v[4:7], v[152:155], v[68:71]
	s_waitcnt vmcnt(9)
	v_mfma_f32_16x16x32_bf16 v[64:67], v[8:11], v[152:155], v[64:67]
	s_waitcnt vmcnt(8)
	v_mfma_f32_16x16x32_bf16 v[60:63], v[12:15], v[152:155], v[60:63]
	v_mfma_f32_16x16x32_bf16 v[76:79], v[36:39], v[152:155], v[76:79]
	ds_read_b128 v[152:155], v168 offset:22528
	ds_read_b128 v[174:177], v168 offset:23552
	s_waitcnt lgkmcnt(1)
	v_mfma_f32_16x16x32_bf16 v[156:159], v[24:27], v[152:155], 0
	v_mfma_f32_16x16x32_bf16 v[152:155], v[28:31], v[152:155], 0
	s_waitcnt lgkmcnt(0)
	v_mfma_f32_16x16x32_bf16 v[156:159], v[16:19], v[174:177], v[156:159]
	v_mfma_f32_16x16x32_bf16 v[152:155], v[20:23], v[174:177], v[152:155]
	s_nop 6
	v_max3_f32 v32, v156, v157, v158
	v_max3_f32 v35, v159, v152, v153
	v_max3_f32 v32, v32, v154, v155
	v_max_f32_e32 v32, v32, v35
	v_add_f32_e32 v34, 0x41000000, v172
	v_cmp_gt_f32_e32 vcc, v32, v34
	s_cbranch_vccz .LBB0_367
	v_mov_b32_e32 v34, v32
	s_nop 1
	v_permlane16_swap_b32 v32, v34
	s_nop 0
	v_max_f32_e32 v34, v34, v34
	v_max_f32_e32 v32, v32, v32
	v_max_f32_e32 v32, v32, v34
	v_mov_b32_e32 v34, v32
	s_nop 1
	v_permlane32_swap_b32 v32, v34
	s_nop 0
	v_max3_f32 v34, v172, v32, v34
	v_sub_f32_e32 v32, v172, v34
	v_exp_f32_e32 v32, v32
	v_mov_b32_e32 v172, v34
	v_pk_mul_f32 v[114:115], v[114:115], v[32:33] op_sel_hi:[1,0]
	v_pk_mul_f32 v[112:113], v[112:113], v[32:33] op_sel_hi:[1,0]
	v_pk_mul_f32 v[110:111], v[110:111], v[32:33] op_sel_hi:[1,0]
	v_pk_mul_f32 v[108:109], v[108:109], v[32:33] op_sel_hi:[1,0]
	v_pk_mul_f32 v[106:107], v[106:107], v[32:33] op_sel_hi:[1,0]
	v_pk_mul_f32 v[104:105], v[104:105], v[32:33] op_sel_hi:[1,0]
	v_pk_mul_f32 v[102:103], v[102:103], v[32:33] op_sel_hi:[1,0]
	v_pk_mul_f32 v[100:101], v[100:101], v[32:33] op_sel_hi:[1,0]
	v_pk_mul_f32 v[118:119], v[118:119], v[32:33] op_sel_hi:[1,0]
	v_pk_mul_f32 v[116:117], v[116:117], v[32:33] op_sel_hi:[1,0]
.LBB0_367:
	v_sub_f32_e32 v154, v154, v172
	v_sub_f32_e32 v155, v155, v172
	v_sub_f32_e32 v152, v152, v172
	v_sub_f32_e32 v153, v153, v172
	v_sub_f32_e32 v156, v156, v172
	v_sub_f32_e32 v157, v157, v172
	v_sub_f32_e32 v158, v158, v172
	v_sub_f32_e32 v159, v159, v172
	v_exp_f32_e32 v154, v154
	v_exp_f32_e32 v155, v155
	v_exp_f32_e32 v152, v152
	v_exp_f32_e32 v153, v153
	v_exp_f32_e32 v156, v156
	v_exp_f32_e32 v157, v157
	v_exp_f32_e32 v158, v158
	v_exp_f32_e32 v159, v159
	v_cvt_pk_bf16_f32 v155, v154, v155
	v_cvt_pk_bf16_f32 v154, v152, v153
	v_cvt_pk_bf16_f32 v152, v156, v157
	v_cvt_pk_bf16_f32 v153, v158, v159
	s_nop 1
	v_mfma_f32_16x16x32_bf16 v[112:115], v[0:3], v[152:155], v[112:115]
	v_mfma_f32_16x16x32_bf16 v[108:111], v[4:7], v[152:155], v[108:111]
	v_mfma_f32_16x16x32_bf16 v[104:107], v[8:11], v[152:155], v[104:107]
	v_mfma_f32_16x16x32_bf16 v[100:103], v[12:15], v[152:155], v[100:103]
	v_mfma_f32_16x16x32_bf16 v[116:119], v[36:39], v[152:155], v[116:119]
	ds_read_b128 v[152:155], v168 offset:24576
	ds_read_b128 v[174:177], v168 offset:25600
	s_waitcnt lgkmcnt(1)
	v_mfma_f32_16x16x32_bf16 v[156:159], v[24:27], v[152:155], 0
	v_mfma_f32_16x16x32_bf16 v[152:155], v[28:31], v[152:155], 0
	s_waitcnt lgkmcnt(0)
	v_mfma_f32_16x16x32_bf16 v[156:159], v[16:19], v[174:177], v[156:159]
	v_mfma_f32_16x16x32_bf16 v[152:155], v[20:23], v[174:177], v[152:155]
	s_nop 6
	v_max3_f32 v32, v156, v157, v158
	v_max3_f32 v35, v159, v152, v153
	v_max3_f32 v32, v32, v154, v155
	v_max_f32_e32 v32, v32, v35
	v_add_f32_e32 v34, 0x41000000, v171
	v_cmp_gt_f32_e32 vcc, v32, v34
	s_cbranch_vccz .LBB0_369
	v_mov_b32_e32 v34, v32
	s_nop 1
	v_permlane16_swap_b32 v32, v34
	s_nop 0
	v_max_f32_e32 v34, v34, v34
	v_max_f32_e32 v32, v32, v32
	v_max_f32_e32 v32, v32, v34
	v_mov_b32_e32 v34, v32
	s_nop 1
	v_permlane32_swap_b32 v34, v32
	s_nop 0
	v_max3_f32 v34, v171, v34, v32
	v_sub_f32_e32 v32, v171, v34
	v_exp_f32_e32 v32, v32
	v_mov_b32_e32 v171, v34
	v_pk_mul_f32 v[94:95], v[94:95], v[32:33] op_sel_hi:[1,0]
	v_pk_mul_f32 v[92:93], v[92:93], v[32:33] op_sel_hi:[1,0]
	v_pk_mul_f32 v[90:91], v[90:91], v[32:33] op_sel_hi:[1,0]
	v_pk_mul_f32 v[88:89], v[88:89], v[32:33] op_sel_hi:[1,0]
	v_pk_mul_f32 v[86:87], v[86:87], v[32:33] op_sel_hi:[1,0]
	v_pk_mul_f32 v[84:85], v[84:85], v[32:33] op_sel_hi:[1,0]
	v_pk_mul_f32 v[82:83], v[82:83], v[32:33] op_sel_hi:[1,0]
	v_pk_mul_f32 v[80:81], v[80:81], v[32:33] op_sel_hi:[1,0]
	v_pk_mul_f32 v[98:99], v[98:99], v[32:33] op_sel_hi:[1,0]
	v_pk_mul_f32 v[96:97], v[96:97], v[32:33] op_sel_hi:[1,0]
.LBB0_369:
	v_sub_f32_e32 v154, v154, v171
	v_sub_f32_e32 v155, v155, v171
	v_sub_f32_e32 v152, v152, v171
	v_sub_f32_e32 v153, v153, v171
	v_sub_f32_e32 v156, v156, v171
	v_sub_f32_e32 v157, v157, v171
	v_sub_f32_e32 v158, v158, v171
	v_sub_f32_e32 v159, v159, v171
	v_exp_f32_e32 v154, v154
	v_exp_f32_e32 v155, v155
	v_exp_f32_e32 v152, v152
	v_exp_f32_e32 v153, v153
	v_exp_f32_e32 v156, v156
	v_exp_f32_e32 v157, v157
	v_exp_f32_e32 v158, v158
	v_exp_f32_e32 v159, v159
	v_cvt_pk_bf16_f32 v155, v154, v155
	v_cvt_pk_bf16_f32 v154, v152, v153
	v_cvt_pk_bf16_f32 v152, v156, v157
	v_cvt_pk_bf16_f32 v153, v158, v159
	s_nop 1
	v_mfma_f32_16x16x32_bf16 v[92:95], v[0:3], v[152:155], v[92:95]
	v_mfma_f32_16x16x32_bf16 v[88:91], v[4:7], v[152:155], v[88:91]
	v_mfma_f32_16x16x32_bf16 v[84:87], v[8:11], v[152:155], v[84:87]
	v_mfma_f32_16x16x32_bf16 v[80:83], v[12:15], v[152:155], v[80:83]
	v_mfma_f32_16x16x32_bf16 v[96:99], v[36:39], v[152:155], v[96:99]
	ds_read_b128 v[152:155], v168 offset:26624
	s_waitcnt lgkmcnt(0)
	v_mfma_f32_16x16x32_bf16 v[24:27], v[24:27], v[152:155], 0
	v_mfma_f32_16x16x32_bf16 v[28:31], v[28:31], v[152:155], 0
	ds_read_b128 v[152:155], v168 offset:27648
	s_waitcnt lgkmcnt(0)
	v_mfma_f32_16x16x32_bf16 v[16:19], v[16:19], v[152:155], v[24:27]
	v_mfma_f32_16x16x32_bf16 v[20:23], v[20:23], v[152:155], v[28:31]
	s_nop 6
	v_max3_f32 v24, v16, v17, v18
	v_max3_f32 v26, v19, v20, v21
	v_max3_f32 v24, v24, v22, v23
	v_max_f32_e32 v24, v24, v26
	v_add_f32_e32 v25, 0x41000000, v169
	v_cmp_gt_f32_e32 vcc, v24, v25
	s_cbranch_vccz .LBB0_371
	v_mov_b32_e32 v25, v24
	s_nop 1
	v_permlane16_swap_b32 v24, v25
	s_nop 0
	v_max_f32_e32 v25, v25, v25
	v_max_f32_e32 v24, v24, v24
	v_max_f32_e32 v24, v24, v25
	v_mov_b32_e32 v25, v24
	s_nop 1
	v_permlane32_swap_b32 v24, v25
	s_nop 0
	v_max3_f32 v25, v169, v24, v25
	v_sub_f32_e32 v24, v169, v25
	v_exp_f32_e32 v24, v24
	v_mov_b32_e32 v169, v25
	v_pk_mul_f32 v[54:55], v[54:55], v[24:25] op_sel_hi:[1,0]
	v_pk_mul_f32 v[52:53], v[52:53], v[24:25] op_sel_hi:[1,0]
	v_pk_mul_f32 v[50:51], v[50:51], v[24:25] op_sel_hi:[1,0]
	v_pk_mul_f32 v[48:49], v[48:49], v[24:25] op_sel_hi:[1,0]
	v_pk_mul_f32 v[46:47], v[46:47], v[24:25] op_sel_hi:[1,0]
	v_pk_mul_f32 v[44:45], v[44:45], v[24:25] op_sel_hi:[1,0]
	v_pk_mul_f32 v[42:43], v[42:43], v[24:25] op_sel_hi:[1,0]
	v_pk_mul_f32 v[40:41], v[40:41], v[24:25] op_sel_hi:[1,0]
	v_pk_mul_f32 v[58:59], v[58:59], v[24:25] op_sel_hi:[1,0]
	v_pk_mul_f32 v[56:57], v[56:57], v[24:25] op_sel_hi:[1,0]

.LBB0_373:
	v_sub_f32_e32 v152, v152, v170
	v_sub_f32_e32 v153, v153, v170
	v_sub_f32_e32 v154, v154, v170
	v_sub_f32_e32 v155, v155, v170
	v_sub_f32_e32 v156, v156, v170
	v_sub_f32_e32 v157, v157, v170
	v_sub_f32_e32 v158, v158, v170
	v_sub_f32_e32 v159, v159, v170
	v_exp_f32_e32 v152, v152
	v_exp_f32_e32 v153, v153
	v_exp_f32_e32 v154, v154
	v_exp_f32_e32 v155, v155
	v_exp_f32_e32 v156, v156
	v_exp_f32_e32 v157, v157
	v_exp_f32_e32 v158, v158
	v_exp_f32_e32 v159, v159
	v_cvt_pk_bf16_f32 v152, v152, v153
	v_cvt_pk_bf16_f32 v153, v154, v155
	v_cvt_pk_bf16_f32 v154, v156, v157
	v_cvt_pk_bf16_f32 v155, v158, v159
	s_waitcnt vmcnt(11)
	s_nop 0
	v_mfma_f32_16x16x32_bf16 v[72:75], v[120:123], v[152:155], v[72:75]
	s_waitcnt vmcnt(10)
	v_mfma_f32_16x16x32_bf16 v[68:71], v[124:127], v[152:155], v[68:71]
	s_waitcnt vmcnt(9)
	v_mfma_f32_16x16x32_bf16 v[64:67], v[128:131], v[152:155], v[64:67]
	s_waitcnt vmcnt(8)
	v_mfma_f32_16x16x32_bf16 v[60:63], v[132:135], v[152:155], v[60:63]
	v_mfma_f32_16x16x32_bf16 v[76:79], v[36:39], v[152:155], v[76:79]
	ds_read_b128 v[152:155], v168 offset:22528
	ds_read_b128 v[174:177], v168 offset:23552
	s_waitcnt lgkmcnt(1)
	v_mfma_f32_16x16x32_bf16 v[156:159], v[144:147], v[152:155], 0
	v_mfma_f32_16x16x32_bf16 v[152:155], v[148:151], v[152:155], 0
	s_waitcnt lgkmcnt(0)
	v_mfma_f32_16x16x32_bf16 v[156:159], v[140:143], v[174:177], v[156:159]
	v_mfma_f32_16x16x32_bf16 v[152:155], v[136:139], v[174:177], v[152:155]
	s_nop 6
	v_max3_f32 v32, v156, v157, v158
	v_max3_f32 v35, v159, v152, v153
	v_max3_f32 v32, v32, v154, v155
	v_max_f32_e32 v32, v32, v35
	v_add_f32_e32 v34, 0x41000000, v172
	v_cmp_gt_f32_e32 vcc, v32, v34
	s_cbranch_vccz .LBB0_375
	v_mov_b32_e32 v34, v32
	s_nop 1
	v_permlane16_swap_b32 v32, v34
	s_nop 0
	v_max_f32_e32 v34, v34, v34
	v_max_f32_e32 v32, v32, v32
	v_max_f32_e32 v32, v32, v34
	v_mov_b32_e32 v34, v32
	s_nop 1
	v_permlane32_swap_b32 v32, v34
	s_nop 0
	v_max3_f32 v34, v172, v32, v34
	v_sub_f32_e32 v32, v172, v34
	v_exp_f32_e32 v32, v32
	v_mov_b32_e32 v172, v34
	v_pk_mul_f32 v[114:115], v[114:115], v[32:33] op_sel_hi:[1,0]
	v_pk_mul_f32 v[112:113], v[112:113], v[32:33] op_sel_hi:[1,0]
	v_pk_mul_f32 v[110:111], v[110:111], v[32:33] op_sel_hi:[1,0]
	v_pk_mul_f32 v[108:109], v[108:109], v[32:33] op_sel_hi:[1,0]
	v_pk_mul_f32 v[106:107], v[106:107], v[32:33] op_sel_hi:[1,0]
	v_pk_mul_f32 v[104:105], v[104:105], v[32:33] op_sel_hi:[1,0]
	v_pk_mul_f32 v[102:103], v[102:103], v[32:33] op_sel_hi:[1,0]
	v_pk_mul_f32 v[100:101], v[100:101], v[32:33] op_sel_hi:[1,0]
	v_pk_mul_f32 v[118:119], v[118:119], v[32:33] op_sel_hi:[1,0]
	v_pk_mul_f32 v[116:117], v[116:117], v[32:33] op_sel_hi:[1,0]
.LBB0_375:
	v_sub_f32_e32 v154, v154, v172
	v_sub_f32_e32 v155, v155, v172
	v_sub_f32_e32 v152, v152, v172
	v_sub_f32_e32 v153, v153, v172
	v_sub_f32_e32 v156, v156, v172
	v_sub_f32_e32 v157, v157, v172
	v_sub_f32_e32 v158, v158, v172
	v_sub_f32_e32 v159, v159, v172
	v_exp_f32_e32 v154, v154
	v_exp_f32_e32 v155, v155
	v_exp_f32_e32 v152, v152
	v_exp_f32_e32 v153, v153
	v_exp_f32_e32 v156, v156
	v_exp_f32_e32 v157, v157
	v_exp_f32_e32 v158, v158
	v_exp_f32_e32 v159, v159
	v_cvt_pk_bf16_f32 v155, v154, v155
	v_cvt_pk_bf16_f32 v154, v152, v153
	v_cvt_pk_bf16_f32 v152, v156, v157
	v_cvt_pk_bf16_f32 v153, v158, v159
	s_nop 1
	v_mfma_f32_16x16x32_bf16 v[112:115], v[120:123], v[152:155], v[112:115]
	v_mfma_f32_16x16x32_bf16 v[108:111], v[124:127], v[152:155], v[108:111]
	v_mfma_f32_16x16x32_bf16 v[104:107], v[128:131], v[152:155], v[104:107]
	v_mfma_f32_16x16x32_bf16 v[100:103], v[132:135], v[152:155], v[100:103]
	v_mfma_f32_16x16x32_bf16 v[116:119], v[36:39], v[152:155], v[116:119]
	ds_read_b128 v[152:155], v168 offset:24576
	ds_read_b128 v[174:177], v168 offset:25600
	s_waitcnt lgkmcnt(1)
	v_mfma_f32_16x16x32_bf16 v[156:159], v[144:147], v[152:155], 0
	v_mfma_f32_16x16x32_bf16 v[152:155], v[148:151], v[152:155], 0
	s_waitcnt lgkmcnt(0)
	v_mfma_f32_16x16x32_bf16 v[156:159], v[140:143], v[174:177], v[156:159]
	v_mfma_f32_16x16x32_bf16 v[152:155], v[136:139], v[174:177], v[152:155]
	s_nop 6
	v_max3_f32 v32, v156, v157, v158
	v_max3_f32 v35, v159, v152, v153
	v_max3_f32 v32, v32, v154, v155
	v_max_f32_e32 v32, v32, v35
	v_add_f32_e32 v34, 0x41000000, v171
	v_cmp_gt_f32_e32 vcc, v32, v34
	s_cbranch_vccz .LBB0_377
	v_mov_b32_e32 v34, v32
	s_nop 1
	v_permlane16_swap_b32 v32, v34
	s_nop 0
	v_max_f32_e32 v34, v34, v34
	v_max_f32_e32 v32, v32, v32
	v_max_f32_e32 v32, v32, v34
	v_mov_b32_e32 v34, v32
	s_nop 1
	v_permlane32_swap_b32 v32, v34
	s_nop 0
	v_max3_f32 v34, v171, v32, v34
	v_sub_f32_e32 v32, v171, v34
	v_exp_f32_e32 v32, v32
	v_mov_b32_e32 v171, v34
	v_pk_mul_f32 v[94:95], v[94:95], v[32:33] op_sel_hi:[1,0]
	v_pk_mul_f32 v[92:93], v[92:93], v[32:33] op_sel_hi:[1,0]
	v_pk_mul_f32 v[90:91], v[90:91], v[32:33] op_sel_hi:[1,0]
	v_pk_mul_f32 v[88:89], v[88:89], v[32:33] op_sel_hi:[1,0]
	v_pk_mul_f32 v[86:87], v[86:87], v[32:33] op_sel_hi:[1,0]
	v_pk_mul_f32 v[84:85], v[84:85], v[32:33] op_sel_hi:[1,0]
	v_pk_mul_f32 v[82:83], v[82:83], v[32:33] op_sel_hi:[1,0]
	v_pk_mul_f32 v[80:81], v[80:81], v[32:33] op_sel_hi:[1,0]
	v_pk_mul_f32 v[98:99], v[98:99], v[32:33] op_sel_hi:[1,0]
	v_pk_mul_f32 v[96:97], v[96:97], v[32:33] op_sel_hi:[1,0]
.LBB0_377:
	v_sub_f32_e32 v154, v154, v171
	v_sub_f32_e32 v155, v155, v171
	v_sub_f32_e32 v152, v152, v171
	v_sub_f32_e32 v153, v153, v171
	v_sub_f32_e32 v156, v156, v171
	v_sub_f32_e32 v157, v157, v171
	v_sub_f32_e32 v158, v158, v171
	v_sub_f32_e32 v159, v159, v171
	v_exp_f32_e32 v154, v154
	v_exp_f32_e32 v155, v155
	v_exp_f32_e32 v152, v152
	v_exp_f32_e32 v153, v153
	v_exp_f32_e32 v156, v156
	v_exp_f32_e32 v157, v157
	v_exp_f32_e32 v158, v158
	v_exp_f32_e32 v159, v159
	v_cvt_pk_bf16_f32 v155, v154, v155
	v_cvt_pk_bf16_f32 v154, v152, v153
	v_cvt_pk_bf16_f32 v152, v156, v157
	v_cvt_pk_bf16_f32 v153, v158, v159
	s_nop 1
	v_mfma_f32_16x16x32_bf16 v[92:95], v[120:123], v[152:155], v[92:95]
	v_mfma_f32_16x16x32_bf16 v[88:91], v[124:127], v[152:155], v[88:91]
	v_mfma_f32_16x16x32_bf16 v[84:87], v[128:131], v[152:155], v[84:87]
	v_mfma_f32_16x16x32_bf16 v[80:83], v[132:135], v[152:155], v[80:83]
	v_mfma_f32_16x16x32_bf16 v[96:99], v[36:39], v[152:155], v[96:99]
	ds_read_b128 v[152:155], v168 offset:26624
	s_waitcnt lgkmcnt(0)
	v_mfma_f32_16x16x32_bf16 v[144:147], v[144:147], v[152:155], 0
	v_mfma_f32_16x16x32_bf16 v[148:151], v[148:151], v[152:155], 0
	ds_read_b128 v[152:155], v168 offset:27648
	s_waitcnt lgkmcnt(0)
	v_mfma_f32_16x16x32_bf16 v[140:143], v[140:143], v[152:155], v[144:147]
	v_mfma_f32_16x16x32_bf16 v[136:139], v[136:139], v[152:155], v[148:151]
	s_nop 6
	v_max3_f32 v32, v140, v141, v142
	v_max3_f32 v35, v143, v136, v137
	v_max3_f32 v32, v32, v138, v139
	v_max_f32_e32 v32, v32, v35
	v_add_f32_e32 v34, 0x41000000, v169
	v_cmp_gt_f32_e32 vcc, v32, v34
	s_cbranch_vccz .LBB0_362
	v_mov_b32_e32 v34, v32
	s_nop 1
	v_permlane16_swap_b32 v32, v34
	s_nop 0
	v_max_f32_e32 v34, v34, v34
	v_max_f32_e32 v32, v32, v32
	v_max_f32_e32 v32, v32, v34
	v_mov_b32_e32 v34, v32
	s_nop 1
	v_permlane32_swap_b32 v32, v34
	s_nop 0
	v_max3_f32 v34, v169, v32, v34
	v_sub_f32_e32 v32, v169, v34
	v_exp_f32_e32 v32, v32
	v_mov_b32_e32 v169, v34
	v_pk_mul_f32 v[54:55], v[54:55], v[32:33] op_sel_hi:[1,0]
	v_pk_mul_f32 v[52:53], v[52:53], v[32:33] op_sel_hi:[1,0]
	v_pk_mul_f32 v[50:51], v[50:51], v[32:33] op_sel_hi:[1,0]
	v_pk_mul_f32 v[48:49], v[48:49], v[32:33] op_sel_hi:[1,0]
	v_pk_mul_f32 v[46:47], v[46:47], v[32:33] op_sel_hi:[1,0]
	v_pk_mul_f32 v[44:45], v[44:45], v[32:33] op_sel_hi:[1,0]
	v_pk_mul_f32 v[42:43], v[42:43], v[32:33] op_sel_hi:[1,0]
	v_pk_mul_f32 v[40:41], v[40:41], v[32:33] op_sel_hi:[1,0]
	v_pk_mul_f32 v[58:59], v[58:59], v[32:33] op_sel_hi:[1,0]
	v_pk_mul_f32 v[56:57], v[56:57], v[32:33] op_sel_hi:[1,0]
	s_branch .LBB0_362

.LBB0_381:
	v_sub_f32_e32 v58, v58, v168
	v_sub_f32_e32 v59, v59, v168
	v_sub_f32_e32 v56, v56, v168
	v_sub_f32_e32 v57, v57, v168
	v_sub_f32_e32 v60, v60, v168
	v_sub_f32_e32 v61, v61, v168
	v_sub_f32_e32 v62, v62, v168
	v_sub_f32_e32 v63, v63, v168
	v_exp_f32_e32 v58, v58
	v_exp_f32_e32 v59, v59
	v_exp_f32_e32 v56, v56
	v_exp_f32_e32 v57, v57
	v_exp_f32_e32 v60, v60
	v_exp_f32_e32 v61, v61
	v_exp_f32_e32 v62, v62
	v_exp_f32_e32 v63, v63
	v_mov_b32_e32 v37, v36
	v_mov_b32_e32 v38, v36
	v_mov_b32_e32 v39, v36
	v_cvt_pk_bf16_f32 v59, v58, v59
	v_cvt_pk_bf16_f32 v58, v56, v57
	v_cvt_pk_bf16_f32 v56, v60, v61
	v_cvt_pk_bf16_f32 v57, v62, v63
	s_nop 1
	v_mfma_f32_16x16x32_bf16 v[84:87], v[40:43], v[56:59], v[84:87]
	v_mfma_f32_16x16x32_bf16 v[80:83], v[44:47], v[56:59], v[80:83]
	v_mfma_f32_16x16x32_bf16 v[76:79], v[48:51], v[56:59], v[76:79]
	v_mfma_f32_16x16x32_bf16 v[72:75], v[52:55], v[56:59], v[72:75]
	v_mfma_f32_16x16x32_bf16 v[88:91], v[36:39], v[56:59], v[88:91]
	s_add_i32 s25, s25, 2
	s_add_u32 s26, s26, 0x10000
	s_addc_u32 s27, s27, 0
	s_add_u32 s34, s34, 0x10000
	s_addc_u32 s35, s35, 0
	s_cmp_lt_u32 s30, 6
	s_cbranch_scc0 .LBB0_398

.LBB0_384:
	v_sub_f32_e32 v152, v152, v171
	v_sub_f32_e32 v153, v153, v171
	v_sub_f32_e32 v154, v154, v171
	v_sub_f32_e32 v155, v155, v171
	v_sub_f32_e32 v156, v156, v171
	v_sub_f32_e32 v157, v157, v171
	v_sub_f32_e32 v158, v158, v171
	v_sub_f32_e32 v159, v159, v171
	v_exp_f32_e32 v152, v152
	v_exp_f32_e32 v153, v153
	v_exp_f32_e32 v154, v154
	v_exp_f32_e32 v155, v155
	v_exp_f32_e32 v156, v156
	v_exp_f32_e32 v157, v157
	v_exp_f32_e32 v158, v158
	v_exp_f32_e32 v159, v159
	v_mov_b32_e32 v37, v36
	v_mov_b32_e32 v38, v36
	v_mov_b32_e32 v39, v36
	v_cvt_pk_bf16_f32 v152, v152, v153
	v_cvt_pk_bf16_f32 v153, v154, v155
	v_cvt_pk_bf16_f32 v154, v156, v157
	v_cvt_pk_bf16_f32 v155, v158, v159
	s_waitcnt vmcnt(11)
	s_nop 0
	v_mfma_f32_16x16x32_bf16 v[144:147], v[0:3], v[152:155], v[144:147]
	s_waitcnt vmcnt(10)
	v_mfma_f32_16x16x32_bf16 v[140:143], v[4:7], v[152:155], v[140:143]
	s_waitcnt vmcnt(9)
	v_mfma_f32_16x16x32_bf16 v[136:139], v[8:11], v[152:155], v[136:139]
	s_waitcnt vmcnt(8)
	v_mfma_f32_16x16x32_bf16 v[132:135], v[12:15], v[152:155], v[132:135]
	v_mfma_f32_16x16x32_bf16 v[148:151], v[36:39], v[152:155], v[148:151]
	ds_read_b128 v[152:155], v167 offset:22528
	ds_read_b128 v[172:175], v167 offset:23552
	s_waitcnt lgkmcnt(1)
	v_mfma_f32_16x16x32_bf16 v[156:159], v[20:23], v[152:155], 0
	v_mfma_f32_16x16x32_bf16 v[152:155], v[28:31], v[152:155], 0
	s_waitcnt lgkmcnt(0)
	v_mfma_f32_16x16x32_bf16 v[156:159], v[16:19], v[172:175], v[156:159]
	v_mfma_f32_16x16x32_bf16 v[152:155], v[24:27], v[172:175], v[152:155]
	s_nop 6
	v_max3_f32 v32, v156, v157, v158
	v_max3_f32 v35, v159, v152, v153
	v_max3_f32 v32, v32, v154, v155
	v_max_f32_e32 v32, v32, v35
	v_add_f32_e32 v34, 0x41000000, v170
	v_cmp_gt_f32_e32 vcc, v32, v34
	s_cbranch_vccz .LBB0_386
	v_mov_b32_e32 v34, v32
	s_nop 1
	v_permlane16_swap_b32 v32, v34
	s_nop 0
	v_max_f32_e32 v34, v34, v34
	v_max_f32_e32 v32, v32, v32
	v_max_f32_e32 v32, v32, v34
	v_mov_b32_e32 v34, v32
	s_nop 1
	v_permlane32_swap_b32 v32, v34
	s_nop 0
	v_max3_f32 v34, v170, v32, v34
	v_sub_f32_e32 v32, v170, v34
	v_exp_f32_e32 v32, v32
	v_mov_b32_e32 v170, v34
	v_pk_mul_f32 v[126:127], v[126:127], v[32:33] op_sel_hi:[1,0]
	v_pk_mul_f32 v[124:125], v[124:125], v[32:33] op_sel_hi:[1,0]
	v_pk_mul_f32 v[122:123], v[122:123], v[32:33] op_sel_hi:[1,0]
	v_pk_mul_f32 v[120:121], v[120:121], v[32:33] op_sel_hi:[1,0]
	v_pk_mul_f32 v[118:119], v[118:119], v[32:33] op_sel_hi:[1,0]
	v_pk_mul_f32 v[116:117], v[116:117], v[32:33] op_sel_hi:[1,0]
	v_pk_mul_f32 v[114:115], v[114:115], v[32:33] op_sel_hi:[1,0]
	v_pk_mul_f32 v[112:113], v[112:113], v[32:33] op_sel_hi:[1,0]
	v_pk_mul_f32 v[130:131], v[130:131], v[32:33] op_sel_hi:[1,0]
	v_pk_mul_f32 v[128:129], v[128:129], v[32:33] op_sel_hi:[1,0]
.LBB0_386:
	v_sub_f32_e32 v154, v154, v170
	v_sub_f32_e32 v155, v155, v170
	v_sub_f32_e32 v152, v152, v170
	v_sub_f32_e32 v153, v153, v170
	v_sub_f32_e32 v156, v156, v170
	v_sub_f32_e32 v157, v157, v170
	v_sub_f32_e32 v158, v158, v170
	v_sub_f32_e32 v159, v159, v170
	v_exp_f32_e32 v154, v154
	v_exp_f32_e32 v155, v155
	v_exp_f32_e32 v152, v152
	v_exp_f32_e32 v153, v153
	v_exp_f32_e32 v156, v156
	v_exp_f32_e32 v157, v157
	v_exp_f32_e32 v158, v158
	v_exp_f32_e32 v159, v159
	v_cvt_pk_bf16_f32 v155, v154, v155
	v_cvt_pk_bf16_f32 v154, v152, v153
	v_cvt_pk_bf16_f32 v152, v156, v157
	v_cvt_pk_bf16_f32 v153, v158, v159
	s_nop 1
	v_mfma_f32_16x16x32_bf16 v[124:127], v[0:3], v[152:155], v[124:127]
	v_mfma_f32_16x16x32_bf16 v[120:123], v[4:7], v[152:155], v[120:123]
	v_mfma_f32_16x16x32_bf16 v[116:119], v[8:11], v[152:155], v[116:119]
	v_mfma_f32_16x16x32_bf16 v[112:115], v[12:15], v[152:155], v[112:115]
	v_mfma_f32_16x16x32_bf16 v[128:131], v[36:39], v[152:155], v[128:131]
	ds_read_b128 v[152:155], v167 offset:24576
	ds_read_b128 v[172:175], v167 offset:25600
	s_waitcnt lgkmcnt(1)
	v_mfma_f32_16x16x32_bf16 v[156:159], v[20:23], v[152:155], 0
	v_mfma_f32_16x16x32_bf16 v[152:155], v[28:31], v[152:155], 0
	s_waitcnt lgkmcnt(0)
	v_mfma_f32_16x16x32_bf16 v[156:159], v[16:19], v[172:175], v[156:159]
	v_mfma_f32_16x16x32_bf16 v[152:155], v[24:27], v[172:175], v[152:155]
	s_nop 6
	v_max3_f32 v32, v156, v157, v158
	v_max3_f32 v35, v159, v152, v153
	v_max3_f32 v32, v32, v154, v155
	v_max_f32_e32 v32, v32, v35
	v_add_f32_e32 v34, 0x41000000, v169
	v_cmp_gt_f32_e32 vcc, v32, v34
	s_cbranch_vccz .LBB0_388
	v_mov_b32_e32 v34, v32
	s_nop 1
	v_permlane16_swap_b32 v32, v34
	s_nop 0
	v_max_f32_e32 v34, v34, v34
	v_max_f32_e32 v32, v32, v32
	v_max_f32_e32 v32, v32, v34
	v_mov_b32_e32 v34, v32
	s_nop 1
	v_permlane32_swap_b32 v32, v34
	s_nop 0
	v_max3_f32 v34, v169, v32, v34
	v_sub_f32_e32 v32, v169, v34
	v_exp_f32_e32 v32, v32
	v_mov_b32_e32 v169, v34
	v_pk_mul_f32 v[106:107], v[106:107], v[32:33] op_sel_hi:[1,0]
	v_pk_mul_f32 v[104:105], v[104:105], v[32:33] op_sel_hi:[1,0]
	v_pk_mul_f32 v[102:103], v[102:103], v[32:33] op_sel_hi:[1,0]
	v_pk_mul_f32 v[100:101], v[100:101], v[32:33] op_sel_hi:[1,0]
	v_pk_mul_f32 v[98:99], v[98:99], v[32:33] op_sel_hi:[1,0]
	v_pk_mul_f32 v[96:97], v[96:97], v[32:33] op_sel_hi:[1,0]
	v_pk_mul_f32 v[94:95], v[94:95], v[32:33] op_sel_hi:[1,0]
	v_pk_mul_f32 v[92:93], v[92:93], v[32:33] op_sel_hi:[1,0]
	v_pk_mul_f32 v[110:111], v[110:111], v[32:33] op_sel_hi:[1,0]
	v_pk_mul_f32 v[108:109], v[108:109], v[32:33] op_sel_hi:[1,0]
.LBB0_388:
	v_sub_f32_e32 v154, v154, v169
	v_sub_f32_e32 v155, v155, v169
	v_sub_f32_e32 v152, v152, v169
	v_sub_f32_e32 v153, v153, v169
	v_sub_f32_e32 v156, v156, v169
	v_sub_f32_e32 v157, v157, v169
	v_sub_f32_e32 v158, v158, v169
	v_sub_f32_e32 v159, v159, v169
	v_exp_f32_e32 v154, v154
	v_exp_f32_e32 v155, v155
	v_exp_f32_e32 v152, v152
	v_exp_f32_e32 v153, v153
	v_exp_f32_e32 v156, v156
	v_exp_f32_e32 v157, v157
	v_exp_f32_e32 v158, v158
	v_exp_f32_e32 v159, v159
	v_cvt_pk_bf16_f32 v155, v154, v155
	v_cvt_pk_bf16_f32 v154, v152, v153
	v_cvt_pk_bf16_f32 v152, v156, v157
	v_cvt_pk_bf16_f32 v153, v158, v159
	s_nop 1
	v_mfma_f32_16x16x32_bf16 v[104:107], v[0:3], v[152:155], v[104:107]
	v_mfma_f32_16x16x32_bf16 v[100:103], v[4:7], v[152:155], v[100:103]
	v_mfma_f32_16x16x32_bf16 v[96:99], v[8:11], v[152:155], v[96:99]
	v_mfma_f32_16x16x32_bf16 v[92:95], v[12:15], v[152:155], v[92:95]
	v_mfma_f32_16x16x32_bf16 v[108:111], v[36:39], v[152:155], v[108:111]
	ds_read_b128 v[152:155], v167 offset:26624
	s_waitcnt lgkmcnt(0)
	v_mfma_f32_16x16x32_bf16 v[20:23], v[20:23], v[152:155], 0
	v_mfma_f32_16x16x32_bf16 v[28:31], v[28:31], v[152:155], 0
	ds_read_b128 v[152:155], v167 offset:27648
	s_waitcnt lgkmcnt(0)
	v_mfma_f32_16x16x32_bf16 v[16:19], v[16:19], v[152:155], v[20:23]
	s_nop 7
	v_mfma_f32_16x16x32_bf16 v[20:23], v[24:27], v[152:155], v[28:31]
	s_nop 7
	v_max3_f32 v24, v16, v17, v18
	v_max3_f32 v25, v19, v20, v21
	v_max3_f32 v24, v24, v22, v23
	v_max_f32_e32 v24, v24, v25
	v_add_f32_e32 v25, 0x41000000, v168
	v_cmp_gt_f32_e32 vcc, v24, v25
	s_cbranch_vccz .LBB0_390
	v_mov_b32_e32 v25, v24
	s_nop 1
	v_permlane16_swap_b32 v24, v25
	s_nop 0
	v_max_f32_e32 v25, v25, v25
	v_max_f32_e32 v24, v24, v24
	v_max_f32_e32 v24, v24, v25
	v_mov_b32_e32 v25, v24
	s_nop 1
	v_permlane32_swap_b32 v24, v25
	s_nop 0
	v_max3_f32 v25, v168, v24, v25
	v_sub_f32_e32 v24, v168, v25
	v_exp_f32_e32 v24, v24
	v_mov_b32_e32 v168, v25
	v_pk_mul_f32 v[86:87], v[86:87], v[24:25] op_sel_hi:[1,0]
	v_pk_mul_f32 v[84:85], v[84:85], v[24:25] op_sel_hi:[1,0]
	v_pk_mul_f32 v[82:83], v[82:83], v[24:25] op_sel_hi:[1,0]
	v_pk_mul_f32 v[80:81], v[80:81], v[24:25] op_sel_hi:[1,0]
	v_pk_mul_f32 v[78:79], v[78:79], v[24:25] op_sel_hi:[1,0]
	v_pk_mul_f32 v[76:77], v[76:77], v[24:25] op_sel_hi:[1,0]
	v_pk_mul_f32 v[74:75], v[74:75], v[24:25] op_sel_hi:[1,0]
	v_pk_mul_f32 v[72:73], v[72:73], v[24:25] op_sel_hi:[1,0]
	v_pk_mul_f32 v[90:91], v[90:91], v[24:25] op_sel_hi:[1,0]
	v_pk_mul_f32 v[88:89], v[88:89], v[24:25] op_sel_hi:[1,0]

.LBB0_392:
	v_sub_f32_e32 v152, v152, v171
	v_sub_f32_e32 v153, v153, v171
	v_sub_f32_e32 v154, v154, v171
	v_sub_f32_e32 v155, v155, v171
	v_sub_f32_e32 v156, v156, v171
	v_sub_f32_e32 v157, v157, v171
	v_sub_f32_e32 v158, v158, v171
	v_sub_f32_e32 v159, v159, v171
	v_exp_f32_e32 v152, v152
	v_exp_f32_e32 v153, v153
	v_exp_f32_e32 v154, v154
	v_exp_f32_e32 v155, v155
	v_exp_f32_e32 v156, v156
	v_exp_f32_e32 v157, v157
	v_exp_f32_e32 v158, v158
	v_exp_f32_e32 v159, v159
	v_cvt_pk_bf16_f32 v152, v152, v153
	v_cvt_pk_bf16_f32 v153, v154, v155
	v_cvt_pk_bf16_f32 v154, v156, v157
	v_cvt_pk_bf16_f32 v155, v158, v159
	s_waitcnt vmcnt(11)
	s_nop 0
	v_mfma_f32_16x16x32_bf16 v[144:147], v[40:43], v[152:155], v[144:147]
	s_waitcnt vmcnt(10)
	v_mfma_f32_16x16x32_bf16 v[140:143], v[44:47], v[152:155], v[140:143]
	s_waitcnt vmcnt(9)
	v_mfma_f32_16x16x32_bf16 v[136:139], v[48:51], v[152:155], v[136:139]
	s_waitcnt vmcnt(8)
	v_mfma_f32_16x16x32_bf16 v[132:135], v[52:55], v[152:155], v[132:135]
	v_mfma_f32_16x16x32_bf16 v[148:151], v[36:39], v[152:155], v[148:151]
	ds_read_b128 v[152:155], v167 offset:22528
	ds_read_b128 v[172:175], v167 offset:23552
	s_waitcnt lgkmcnt(1)
	v_mfma_f32_16x16x32_bf16 v[156:159], v[64:67], v[152:155], 0
	v_mfma_f32_16x16x32_bf16 v[152:155], v[68:71], v[152:155], 0
	s_waitcnt lgkmcnt(0)
	v_mfma_f32_16x16x32_bf16 v[156:159], v[60:63], v[172:175], v[156:159]
	v_mfma_f32_16x16x32_bf16 v[152:155], v[56:59], v[172:175], v[152:155]
	s_nop 6
	v_max3_f32 v32, v156, v157, v158
	v_max3_f32 v35, v159, v152, v153
	v_max3_f32 v32, v32, v154, v155
	v_max_f32_e32 v32, v32, v35
	v_add_f32_e32 v34, 0x41000000, v170
	v_cmp_gt_f32_e32 vcc, v32, v34
	s_cbranch_vccz .LBB0_394
	v_mov_b32_e32 v34, v32
	s_nop 1
	v_permlane16_swap_b32 v32, v34
	s_nop 0
	v_max_f32_e32 v34, v34, v34
	v_max_f32_e32 v32, v32, v32
	v_max_f32_e32 v32, v32, v34
	v_mov_b32_e32 v34, v32
	s_nop 1
	v_permlane32_swap_b32 v32, v34
	s_nop 0
	v_max3_f32 v34, v170, v32, v34
	v_sub_f32_e32 v32, v170, v34
	v_exp_f32_e32 v32, v32
	v_mov_b32_e32 v170, v34
	v_pk_mul_f32 v[126:127], v[126:127], v[32:33] op_sel_hi:[1,0]
	v_pk_mul_f32 v[124:125], v[124:125], v[32:33] op_sel_hi:[1,0]
	v_pk_mul_f32 v[122:123], v[122:123], v[32:33] op_sel_hi:[1,0]
	v_pk_mul_f32 v[120:121], v[120:121], v[32:33] op_sel_hi:[1,0]
	v_pk_mul_f32 v[118:119], v[118:119], v[32:33] op_sel_hi:[1,0]
	v_pk_mul_f32 v[116:117], v[116:117], v[32:33] op_sel_hi:[1,0]
	v_pk_mul_f32 v[114:115], v[114:115], v[32:33] op_sel_hi:[1,0]
	v_pk_mul_f32 v[112:113], v[112:113], v[32:33] op_sel_hi:[1,0]
	v_pk_mul_f32 v[130:131], v[130:131], v[32:33] op_sel_hi:[1,0]
	v_pk_mul_f32 v[128:129], v[128:129], v[32:33] op_sel_hi:[1,0]
.LBB0_394:
	v_sub_f32_e32 v154, v154, v170
	v_sub_f32_e32 v155, v155, v170
	v_sub_f32_e32 v152, v152, v170
	v_sub_f32_e32 v153, v153, v170
	v_sub_f32_e32 v156, v156, v170
	v_sub_f32_e32 v157, v157, v170
	v_sub_f32_e32 v158, v158, v170
	v_sub_f32_e32 v159, v159, v170
	v_exp_f32_e32 v154, v154
	v_exp_f32_e32 v155, v155
	v_exp_f32_e32 v152, v152
	v_exp_f32_e32 v153, v153
	v_exp_f32_e32 v156, v156
	v_exp_f32_e32 v157, v157
	v_exp_f32_e32 v158, v158
	v_exp_f32_e32 v159, v159
	v_cvt_pk_bf16_f32 v155, v154, v155
	v_cvt_pk_bf16_f32 v154, v152, v153
	v_cvt_pk_bf16_f32 v152, v156, v157
	v_cvt_pk_bf16_f32 v153, v158, v159
	s_nop 1
	v_mfma_f32_16x16x32_bf16 v[124:127], v[40:43], v[152:155], v[124:127]
	v_mfma_f32_16x16x32_bf16 v[120:123], v[44:47], v[152:155], v[120:123]
	v_mfma_f32_16x16x32_bf16 v[116:119], v[48:51], v[152:155], v[116:119]
	v_mfma_f32_16x16x32_bf16 v[112:115], v[52:55], v[152:155], v[112:115]
	v_mfma_f32_16x16x32_bf16 v[128:131], v[36:39], v[152:155], v[128:131]
	ds_read_b128 v[152:155], v167 offset:24576
	ds_read_b128 v[172:175], v167 offset:25600
	s_waitcnt lgkmcnt(1)
	v_mfma_f32_16x16x32_bf16 v[156:159], v[64:67], v[152:155], 0
	v_mfma_f32_16x16x32_bf16 v[152:155], v[68:71], v[152:155], 0
	s_waitcnt lgkmcnt(0)
	v_mfma_f32_16x16x32_bf16 v[156:159], v[60:63], v[172:175], v[156:159]
	v_mfma_f32_16x16x32_bf16 v[152:155], v[56:59], v[172:175], v[152:155]
	s_nop 6
	v_max3_f32 v32, v156, v157, v158
	v_max3_f32 v35, v159, v152, v153
	v_max3_f32 v32, v32, v154, v155
	v_max_f32_e32 v32, v32, v35
	v_add_f32_e32 v34, 0x41000000, v169
	v_cmp_gt_f32_e32 vcc, v32, v34
	s_cbranch_vccz .LBB0_396
	v_mov_b32_e32 v34, v32
	s_nop 1
	v_permlane16_swap_b32 v32, v34
	s_nop 0
	v_max_f32_e32 v34, v34, v34
	v_max_f32_e32 v32, v32, v32
	v_max_f32_e32 v32, v32, v34
	v_mov_b32_e32 v34, v32
	s_nop 1
	v_permlane32_swap_b32 v34, v32
	s_nop 0
	v_max3_f32 v34, v169, v34, v32
	v_sub_f32_e32 v32, v169, v34
	v_exp_f32_e32 v32, v32
	v_mov_b32_e32 v169, v34
	v_pk_mul_f32 v[106:107], v[106:107], v[32:33] op_sel_hi:[1,0]
	v_pk_mul_f32 v[104:105], v[104:105], v[32:33] op_sel_hi:[1,0]
	v_pk_mul_f32 v[102:103], v[102:103], v[32:33] op_sel_hi:[1,0]
	v_pk_mul_f32 v[100:101], v[100:101], v[32:33] op_sel_hi:[1,0]
	v_pk_mul_f32 v[98:99], v[98:99], v[32:33] op_sel_hi:[1,0]
	v_pk_mul_f32 v[96:97], v[96:97], v[32:33] op_sel_hi:[1,0]
	v_pk_mul_f32 v[94:95], v[94:95], v[32:33] op_sel_hi:[1,0]
	v_pk_mul_f32 v[92:93], v[92:93], v[32:33] op_sel_hi:[1,0]
	v_pk_mul_f32 v[110:111], v[110:111], v[32:33] op_sel_hi:[1,0]
	v_pk_mul_f32 v[108:109], v[108:109], v[32:33] op_sel_hi:[1,0]
.LBB0_396:
	v_sub_f32_e32 v154, v154, v169
	v_sub_f32_e32 v155, v155, v169
	v_sub_f32_e32 v152, v152, v169
	v_sub_f32_e32 v153, v153, v169
	v_sub_f32_e32 v156, v156, v169
	v_sub_f32_e32 v157, v157, v169
	v_sub_f32_e32 v158, v158, v169
	v_sub_f32_e32 v159, v159, v169
	v_exp_f32_e32 v154, v154
	v_exp_f32_e32 v155, v155
	v_exp_f32_e32 v152, v152
	v_exp_f32_e32 v153, v153
	v_exp_f32_e32 v156, v156
	v_exp_f32_e32 v157, v157
	v_exp_f32_e32 v158, v158
	v_exp_f32_e32 v159, v159
	v_cvt_pk_bf16_f32 v155, v154, v155
	v_cvt_pk_bf16_f32 v154, v152, v153
	v_cvt_pk_bf16_f32 v152, v156, v157
	v_cvt_pk_bf16_f32 v153, v158, v159
	s_nop 1
	v_mfma_f32_16x16x32_bf16 v[104:107], v[40:43], v[152:155], v[104:107]
	v_mfma_f32_16x16x32_bf16 v[100:103], v[44:47], v[152:155], v[100:103]
	v_mfma_f32_16x16x32_bf16 v[96:99], v[48:51], v[152:155], v[96:99]
	v_mfma_f32_16x16x32_bf16 v[92:95], v[52:55], v[152:155], v[92:95]
	v_mfma_f32_16x16x32_bf16 v[108:111], v[36:39], v[152:155], v[108:111]
	ds_read_b128 v[152:155], v167 offset:26624
	s_waitcnt lgkmcnt(0)
	v_mfma_f32_16x16x32_bf16 v[64:67], v[64:67], v[152:155], 0
	v_mfma_f32_16x16x32_bf16 v[68:71], v[68:71], v[152:155], 0
	ds_read_b128 v[152:155], v167 offset:27648
	s_waitcnt lgkmcnt(0)
	v_mfma_f32_16x16x32_bf16 v[60:63], v[60:63], v[152:155], v[64:67]
	v_mfma_f32_16x16x32_bf16 v[56:59], v[56:59], v[152:155], v[68:71]
	s_nop 6
	v_max3_f32 v32, v60, v61, v62
	v_max3_f32 v35, v63, v56, v57
	v_max3_f32 v32, v32, v58, v59
	v_max_f32_e32 v32, v32, v35
	v_add_f32_e32 v34, 0x41000000, v168
	v_cmp_gt_f32_e32 vcc, v32, v34
	s_cbranch_vccz .LBB0_381
	v_mov_b32_e32 v34, v32
	s_nop 1
	v_permlane16_swap_b32 v32, v34
	s_nop 0
	v_max_f32_e32 v34, v34, v34
	v_max_f32_e32 v32, v32, v32
	v_max_f32_e32 v32, v32, v34
	v_mov_b32_e32 v34, v32
	s_nop 1
	v_permlane32_swap_b32 v32, v34
	s_nop 0
	v_max3_f32 v34, v168, v32, v34
	v_sub_f32_e32 v32, v168, v34
	v_exp_f32_e32 v32, v32
	v_mov_b32_e32 v168, v34
	v_pk_mul_f32 v[86:87], v[86:87], v[32:33] op_sel_hi:[1,0]
	v_pk_mul_f32 v[84:85], v[84:85], v[32:33] op_sel_hi:[1,0]
	v_pk_mul_f32 v[82:83], v[82:83], v[32:33] op_sel_hi:[1,0]
	v_pk_mul_f32 v[80:81], v[80:81], v[32:33] op_sel_hi:[1,0]
	v_pk_mul_f32 v[78:79], v[78:79], v[32:33] op_sel_hi:[1,0]
	v_pk_mul_f32 v[76:77], v[76:77], v[32:33] op_sel_hi:[1,0]
	v_pk_mul_f32 v[74:75], v[74:75], v[32:33] op_sel_hi:[1,0]
	v_pk_mul_f32 v[72:73], v[72:73], v[32:33] op_sel_hi:[1,0]
	v_pk_mul_f32 v[90:91], v[90:91], v[32:33] op_sel_hi:[1,0]
	v_pk_mul_f32 v[88:89], v[88:89], v[32:33] op_sel_hi:[1,0]
	s_branch .LBB0_381
